# ATT0-hosted weight transposes: inner loop unrolled so both 16-load batches of an item are in flight together (one memory round trip instead of two)
# speedup vs baseline: 1.0481x; 1.0064x over previous
.LBB0_344:
	s_lshl_b32 s12, s5, 1
	s_lshl_b32 s13, s4, 1
	v_or_b32_e32 v9, s12, v1
	v_or_b32_e32 v11, s13, v0
	s_add_i32 s14, s12, 4
	s_add_i32 s15, s13, 4
	s_add_i32 s16, s12, 8
	s_add_i32 s17, s13, 8
	s_add_i32 s18, s12, 12
	s_add_i32 s19, s13, 12
	s_add_i32 s20, s12, 16
	s_add_i32 s21, s13, 16
	s_add_i32 s22, s12, 20
	s_add_i32 s23, s13, 20
	s_add_i32 s24, s12, 24
	s_add_i32 s25, s13, 24
	s_add_i32 s12, s12, 28
	s_add_i32 s13, s13, 28
	v_add_u32_e32 v17, v9, v7
	v_add_u32_e32 v43, v11, v16
	v_or_b32_e32 v76, s14, v1
	v_or_b32_e32 v77, s15, v0
	v_or_b32_e32 v78, s16, v1
	v_or_b32_e32 v79, s17, v0
	v_or_b32_e32 v80, s18, v1
	v_or_b32_e32 v81, s19, v0
	v_or_b32_e32 v82, s20, v1
	v_or_b32_e32 v83, s21, v0
	v_or_b32_e32 v84, s22, v1
	v_or_b32_e32 v85, s23, v0
	v_or_b32_e32 v86, s24, v1
	v_or_b32_e32 v87, s25, v0
	v_or_b32_e32 v88, s12, v1
	v_or_b32_e32 v89, s13, v0
	v_ashrrev_i32_e32 v48, 31, v43
	v_ashrrev_i32_e32 v49, 31, v17
	v_mul_lo_u32 v90, v3, v17
	v_mad_u64_u32 v[44:45], s[12:13], v2, v17, 0
	v_mul_lo_u32 v17, v13, v43
	v_mad_u64_u32 v[46:47], s[12:13], v12, v43, 0
	v_add_u32_e32 v43, v76, v7
	v_add_u32_e32 v50, v77, v16
	v_add_u32_e32 v52, v78, v7
	v_add_u32_e32 v54, v79, v16
	v_add_u32_e32 v56, v80, v7
	v_add_u32_e32 v58, v81, v16
	v_add_u32_e32 v60, v82, v7
	v_add_u32_e32 v62, v83, v16
	v_add_u32_e32 v64, v84, v7
	v_add_u32_e32 v66, v85, v16
	v_add_u32_e32 v68, v86, v7
	v_add_u32_e32 v70, v87, v16
	v_add_u32_e32 v72, v88, v7
	v_add_u32_e32 v74, v89, v16
	v_mul_lo_u32 v91, v2, v49
	v_mul_lo_u32 v92, v12, v48
	v_ashrrev_i32_e32 v93, 31, v50
	v_ashrrev_i32_e32 v94, 31, v43
	v_ashrrev_i32_e32 v96, 31, v54
	v_ashrrev_i32_e32 v97, 31, v52
	v_ashrrev_i32_e32 v100, 31, v58
	v_ashrrev_i32_e32 v101, 31, v56
	v_ashrrev_i32_e32 v104, 31, v62
	v_ashrrev_i32_e32 v105, 31, v60
	v_ashrrev_i32_e32 v108, 31, v66
	v_ashrrev_i32_e32 v109, 31, v64
	v_ashrrev_i32_e32 v112, 31, v70
	v_ashrrev_i32_e32 v113, 31, v68
	v_ashrrev_i32_e32 v116, 31, v74
	v_ashrrev_i32_e32 v117, 31, v72
	v_mul_lo_u32 v95, v3, v43
	v_mad_u64_u32 v[48:49], s[12:13], v2, v43, 0
	v_mul_lo_u32 v43, v13, v50
	v_mad_u64_u32 v[50:51], s[12:13], v12, v50, 0
	v_mul_lo_u32 v98, v3, v52
	v_mad_u64_u32 v[52:53], s[12:13], v2, v52, 0
	v_mul_lo_u32 v99, v13, v54
	v_mad_u64_u32 v[54:55], s[12:13], v12, v54, 0
	v_mul_lo_u32 v102, v3, v56
	v_mad_u64_u32 v[56:57], s[12:13], v2, v56, 0
	v_mul_lo_u32 v103, v13, v58
	v_mad_u64_u32 v[58:59], s[12:13], v12, v58, 0
	v_mul_lo_u32 v106, v3, v60
	v_mad_u64_u32 v[60:61], s[12:13], v2, v60, 0
	v_mul_lo_u32 v107, v13, v62
	v_mad_u64_u32 v[62:63], s[12:13], v12, v62, 0
	v_mul_lo_u32 v110, v3, v64
	v_mad_u64_u32 v[64:65], s[12:13], v2, v64, 0
	v_mul_lo_u32 v111, v13, v66
	v_mad_u64_u32 v[66:67], s[12:13], v12, v66, 0
	v_mul_lo_u32 v114, v3, v68
	v_mad_u64_u32 v[68:69], s[12:13], v2, v68, 0
	v_mul_lo_u32 v115, v13, v70
	v_mad_u64_u32 v[70:71], s[12:13], v12, v70, 0
	v_mul_lo_u32 v118, v3, v72
	v_mad_u64_u32 v[72:73], s[12:13], v2, v72, 0
	v_mul_lo_u32 v119, v13, v74
	v_mad_u64_u32 v[74:75], s[12:13], v12, v74, 0
	v_add3_u32 v45, v45, v91, v90
	v_add3_u32 v47, v47, v92, v17
	v_mul_lo_u32 v17, v2, v94
	v_mul_lo_u32 v90, v12, v93
	v_mul_lo_u32 v91, v2, v97
	v_mul_lo_u32 v92, v12, v96
	v_mul_lo_u32 v93, v2, v101
	v_mul_lo_u32 v94, v12, v100
	v_mul_lo_u32 v96, v2, v105
	v_mul_lo_u32 v97, v12, v104
	v_mul_lo_u32 v100, v2, v109
	v_mul_lo_u32 v101, v12, v108
	v_mul_lo_u32 v104, v2, v113
	v_mul_lo_u32 v105, v12, v112
	v_mul_lo_u32 v108, v2, v117
	v_mul_lo_u32 v109, v12, v116
	v_lshl_add_u64 v[46:47], v[46:47], 2, v[18:19]
	v_add3_u32 v49, v49, v17, v95
	v_add3_u32 v51, v51, v90, v43
	v_add3_u32 v53, v53, v91, v98
	v_add3_u32 v55, v55, v92, v99
	v_add3_u32 v57, v57, v93, v102
	v_add3_u32 v59, v59, v94, v103
	v_add3_u32 v61, v61, v96, v106
	v_add3_u32 v63, v63, v97, v107
	v_add3_u32 v65, v65, v100, v110
	v_add3_u32 v67, v67, v101, v111
	v_add3_u32 v69, v69, v104, v114
	v_add3_u32 v71, v71, v105, v115
	v_add3_u32 v73, v73, v108, v118
	v_add3_u32 v75, v75, v109, v119
	v_lshl_add_u64 v[44:45], v[44:45], 2, v[18:19]
	v_lshl_add_u64 v[50:51], v[50:51], 2, v[18:19]
	v_lshl_add_u64 v[48:49], v[48:49], 2, v[18:19]
	v_lshl_add_u64 v[54:55], v[54:55], 2, v[18:19]
	v_lshl_add_u64 v[52:53], v[52:53], 2, v[18:19]
	v_lshl_add_u64 v[58:59], v[58:59], 2, v[18:19]
	v_lshl_add_u64 v[56:57], v[56:57], 2, v[18:19]
	v_lshl_add_u64 v[62:63], v[62:63], 2, v[18:19]
	v_lshl_add_u64 v[60:61], v[60:61], 2, v[18:19]
	v_lshl_add_u64 v[66:67], v[66:67], 2, v[18:19]
	v_lshl_add_u64 v[64:65], v[64:65], 2, v[18:19]
	v_lshl_add_u64 v[70:71], v[70:71], 2, v[18:19]
	v_lshl_add_u64 v[68:69], v[68:69], 2, v[18:19]
	v_lshl_add_u64 v[74:75], v[74:75], 2, v[18:19]
	v_lshl_add_u64 v[72:73], v[72:73], 2, v[18:19]
	global_load_dword v17, v[46:47], off nt
	global_load_dword v43, v[44:45], off nt
	global_load_dword v90, v[50:51], off nt
	global_load_dword v91, v[48:49], off nt
	global_load_dword v92, v[54:55], off nt
	global_load_dword v93, v[52:53], off nt
	global_load_dword v94, v[58:59], off nt
	global_load_dword v95, v[56:57], off nt
	global_load_dword v96, v[62:63], off nt
	global_load_dword v97, v[60:61], off nt
	global_load_dword v98, v[66:67], off nt
	global_load_dword v99, v[64:65], off nt
	global_load_dword v100, v[70:71], off nt
	global_load_dword v101, v[68:69], off nt
	global_load_dword v102, v[74:75], off nt
	global_load_dword v103, v[72:73], off nt
	s_add_i32 s4, s4, 16
	s_add_i32 s5, s5, 16
	v_mad_u64_u32 v[44:45], s[12:13], v11, s1, v[6:7]
	v_mad_u64_u32 v[46:47], s[12:13], v9, s1, v[6:7]
	v_mad_u64_u32 v[48:49], s[12:13], v77, s1, v[6:7]
	v_mad_u64_u32 v[50:51], s[12:13], v76, s1, v[6:7]
	v_mad_u64_u32 v[52:53], s[12:13], v79, s1, v[6:7]
	v_mad_u64_u32 v[54:55], s[12:13], v78, s1, v[6:7]
	v_mad_u64_u32 v[56:57], s[12:13], v81, s1, v[6:7]
	v_mad_u64_u32 v[58:59], s[12:13], v80, s1, v[6:7]
	v_mad_u64_u32 v[60:61], s[12:13], v83, s1, v[6:7]
	v_mad_u64_u32 v[62:63], s[12:13], v82, s1, v[6:7]
	v_mad_u64_u32 v[64:65], s[12:13], v85, s1, v[6:7]
	v_mad_u64_u32 v[66:67], s[12:13], v84, s1, v[6:7]
	v_mad_u64_u32 v[68:69], s[12:13], v87, s1, v[6:7]
	v_mad_u64_u32 v[70:71], s[12:13], v86, s1, v[6:7]
	v_mad_u64_u32 v[72:73], s[12:13], v89, s1, v[6:7]
	v_mad_u64_u32 v[74:75], s[12:13], v88, s1, v[6:7]
	s_lshl_b32 s12, s5, 1
	s_lshl_b32 s13, s4, 1
	v_or_b32_e32 v9, s12, v1
	v_or_b32_e32 v11, s13, v0
	s_add_i32 s14, s12, 4
	s_add_i32 s15, s13, 4
	s_add_i32 s16, s12, 8
	s_add_i32 s17, s13, 8
	s_add_i32 s18, s12, 12
	s_add_i32 s19, s13, 12
	s_add_i32 s20, s12, 16
	s_add_i32 s21, s13, 16
	s_add_i32 s22, s12, 20
	s_add_i32 s23, s13, 20
	s_add_i32 s24, s12, 24
	s_add_i32 s25, s13, 24
	s_add_i32 s12, s12, 28
	s_add_i32 s13, s13, 28
	v_add_u32_e32 v120, v9, v7
	v_add_u32_e32 v121, v11, v16
	v_or_b32_e32 v76, s14, v1
	v_or_b32_e32 v77, s15, v0
	v_or_b32_e32 v78, s16, v1
	v_or_b32_e32 v79, s17, v0
	v_or_b32_e32 v80, s18, v1
	v_or_b32_e32 v81, s19, v0
	v_or_b32_e32 v82, s20, v1
	v_or_b32_e32 v83, s21, v0
	v_or_b32_e32 v84, s22, v1
	v_or_b32_e32 v85, s23, v0
	v_or_b32_e32 v86, s24, v1
	v_or_b32_e32 v87, s25, v0
	v_or_b32_e32 v88, s12, v1
	v_or_b32_e32 v89, s13, v0
	v_ashrrev_i32_e32 v190, 31, v121
	v_ashrrev_i32_e32 v191, 31, v120
	v_mul_lo_u32 v122, v3, v120
	v_mad_u64_u32 v[186:187], s[12:13], v2, v120, 0
	v_mul_lo_u32 v120, v13, v121
	v_mad_u64_u32 v[188:189], s[12:13], v12, v121, 0
	v_add_u32_e32 v121, v76, v7
	v_add_u32_e32 v192, v77, v16
	v_add_u32_e32 v194, v78, v7
	v_add_u32_e32 v196, v79, v16
	v_add_u32_e32 v198, v80, v7
	v_add_u32_e32 v200, v81, v16
	v_add_u32_e32 v202, v82, v7
	v_add_u32_e32 v204, v83, v16
	v_add_u32_e32 v206, v84, v7
	v_add_u32_e32 v208, v85, v16
	v_add_u32_e32 v210, v86, v7
	v_add_u32_e32 v212, v87, v16
	v_add_u32_e32 v214, v88, v7
	v_add_u32_e32 v216, v89, v16
	v_mul_lo_u32 v123, v2, v191
	v_mul_lo_u32 v124, v12, v190
	v_ashrrev_i32_e32 v125, 31, v192
	v_ashrrev_i32_e32 v126, 31, v121
	v_ashrrev_i32_e32 v128, 31, v196
	v_ashrrev_i32_e32 v129, 31, v194
	v_ashrrev_i32_e32 v132, 31, v200
	v_ashrrev_i32_e32 v133, 31, v198
	v_ashrrev_i32_e32 v104, 31, v204
	v_ashrrev_i32_e32 v105, 31, v202
	v_ashrrev_i32_e32 v108, 31, v208
	v_ashrrev_i32_e32 v109, 31, v206
	v_ashrrev_i32_e32 v112, 31, v212
	v_ashrrev_i32_e32 v113, 31, v210
	v_ashrrev_i32_e32 v116, 31, v216
	v_ashrrev_i32_e32 v117, 31, v214
	v_mul_lo_u32 v127, v3, v121
	v_mad_u64_u32 v[190:191], s[12:13], v2, v121, 0
	v_mul_lo_u32 v121, v13, v192
	v_mad_u64_u32 v[192:193], s[12:13], v12, v192, 0
	v_mul_lo_u32 v130, v3, v194
	v_mad_u64_u32 v[194:195], s[12:13], v2, v194, 0
	v_mul_lo_u32 v131, v13, v196
	v_mad_u64_u32 v[196:197], s[12:13], v12, v196, 0
	v_mul_lo_u32 v134, v3, v198
	v_mad_u64_u32 v[198:199], s[12:13], v2, v198, 0
	v_mul_lo_u32 v135, v13, v200
	v_mad_u64_u32 v[200:201], s[12:13], v12, v200, 0
	v_mul_lo_u32 v106, v3, v202
	v_mad_u64_u32 v[202:203], s[12:13], v2, v202, 0
	v_mul_lo_u32 v107, v13, v204
	v_mad_u64_u32 v[204:205], s[12:13], v12, v204, 0
	v_mul_lo_u32 v110, v3, v206
	v_mad_u64_u32 v[206:207], s[12:13], v2, v206, 0
	v_mul_lo_u32 v111, v13, v208
	v_mad_u64_u32 v[208:209], s[12:13], v12, v208, 0
	v_mul_lo_u32 v114, v3, v210
	v_mad_u64_u32 v[210:211], s[12:13], v2, v210, 0
	v_mul_lo_u32 v115, v13, v212
	v_mad_u64_u32 v[212:213], s[12:13], v12, v212, 0
	v_mul_lo_u32 v118, v3, v214
	v_mad_u64_u32 v[214:215], s[12:13], v2, v214, 0
	v_mul_lo_u32 v119, v13, v216
	v_mad_u64_u32 v[216:217], s[12:13], v12, v216, 0
	v_add3_u32 v187, v187, v123, v122
	v_add3_u32 v189, v189, v124, v120
	v_mul_lo_u32 v120, v2, v126
	v_mul_lo_u32 v122, v12, v125
	v_mul_lo_u32 v123, v2, v129
	v_mul_lo_u32 v124, v12, v128
	v_mul_lo_u32 v125, v2, v133
	v_mul_lo_u32 v126, v12, v132
	v_mul_lo_u32 v128, v2, v105
	v_mul_lo_u32 v129, v12, v104
	v_mul_lo_u32 v132, v2, v109
	v_mul_lo_u32 v133, v12, v108
	v_mul_lo_u32 v104, v2, v113
	v_mul_lo_u32 v105, v12, v112
	v_mul_lo_u32 v108, v2, v117
	v_mul_lo_u32 v109, v12, v116
	v_lshl_add_u64 v[188:189], v[188:189], 2, v[18:19]
	v_add3_u32 v191, v191, v120, v127
	v_add3_u32 v193, v193, v122, v121
	v_add3_u32 v195, v195, v123, v130
	v_add3_u32 v197, v197, v124, v131
	v_add3_u32 v199, v199, v125, v134
	v_add3_u32 v201, v201, v126, v135
	v_add3_u32 v203, v203, v128, v106
	v_add3_u32 v205, v205, v129, v107
	v_add3_u32 v207, v207, v132, v110
	v_add3_u32 v209, v209, v133, v111
	v_add3_u32 v211, v211, v104, v114
	v_add3_u32 v213, v213, v105, v115
	v_add3_u32 v215, v215, v108, v118
	v_add3_u32 v217, v217, v109, v119
	v_lshl_add_u64 v[186:187], v[186:187], 2, v[18:19]
	v_lshl_add_u64 v[192:193], v[192:193], 2, v[18:19]
	v_lshl_add_u64 v[190:191], v[190:191], 2, v[18:19]
	v_lshl_add_u64 v[196:197], v[196:197], 2, v[18:19]
	v_lshl_add_u64 v[194:195], v[194:195], 2, v[18:19]
	v_lshl_add_u64 v[200:201], v[200:201], 2, v[18:19]
	v_lshl_add_u64 v[198:199], v[198:199], 2, v[18:19]
	v_lshl_add_u64 v[204:205], v[204:205], 2, v[18:19]
	v_lshl_add_u64 v[202:203], v[202:203], 2, v[18:19]
	v_lshl_add_u64 v[208:209], v[208:209], 2, v[18:19]
	v_lshl_add_u64 v[206:207], v[206:207], 2, v[18:19]
	v_lshl_add_u64 v[212:213], v[212:213], 2, v[18:19]
	v_lshl_add_u64 v[210:211], v[210:211], 2, v[18:19]
	v_lshl_add_u64 v[216:217], v[216:217], 2, v[18:19]
	v_lshl_add_u64 v[214:215], v[214:215], 2, v[18:19]
	global_load_dword v120, v[188:189], off nt
	global_load_dword v121, v[186:187], off nt
	global_load_dword v122, v[192:193], off nt
	global_load_dword v123, v[190:191], off nt
	global_load_dword v124, v[196:197], off nt
	global_load_dword v125, v[194:195], off nt
	global_load_dword v126, v[200:201], off nt
	global_load_dword v127, v[198:199], off nt
	global_load_dword v128, v[204:205], off nt
	global_load_dword v129, v[202:203], off nt
	global_load_dword v130, v[208:209], off nt
	global_load_dword v131, v[206:207], off nt
	global_load_dword v132, v[212:213], off nt
	global_load_dword v133, v[210:211], off nt
	global_load_dword v134, v[216:217], off nt
	global_load_dword v135, v[214:215], off nt
	s_add_i32 s4, s4, 16
	s_add_i32 s5, s5, 16
	s_mov_b32 s11, 0
	v_mad_u64_u32 v[186:187], s[12:13], v11, s1, v[6:7]
	v_mad_u64_u32 v[188:189], s[12:13], v9, s1, v[6:7]
	v_mad_u64_u32 v[190:191], s[12:13], v77, s1, v[6:7]
	v_mad_u64_u32 v[192:193], s[12:13], v76, s1, v[6:7]
	v_mad_u64_u32 v[194:195], s[12:13], v79, s1, v[6:7]
	v_mad_u64_u32 v[196:197], s[12:13], v78, s1, v[6:7]
	v_mad_u64_u32 v[198:199], s[12:13], v81, s1, v[6:7]
	v_mad_u64_u32 v[200:201], s[12:13], v80, s1, v[6:7]
	v_mad_u64_u32 v[202:203], s[12:13], v83, s1, v[6:7]
	v_mad_u64_u32 v[204:205], s[12:13], v82, s1, v[6:7]
	v_mad_u64_u32 v[206:207], s[12:13], v85, s1, v[6:7]
	v_mad_u64_u32 v[208:209], s[12:13], v84, s1, v[6:7]
	v_mad_u64_u32 v[210:211], s[12:13], v87, s1, v[6:7]
	v_mad_u64_u32 v[212:213], s[12:13], v86, s1, v[6:7]
	v_mad_u64_u32 v[214:215], s[12:13], v89, s1, v[6:7]
	v_mad_u64_u32 v[216:217], s[12:13], v88, s1, v[6:7]
	s_waitcnt vmcnt(31)
	ds_write_b32 v44, v17
	s_waitcnt vmcnt(30)
	ds_write_b32 v46, v43
	s_waitcnt vmcnt(29)
	ds_write_b32 v48, v90
	s_waitcnt vmcnt(28)
	ds_write_b32 v50, v91
	s_waitcnt vmcnt(27)
	ds_write_b32 v52, v92
	s_waitcnt vmcnt(26)
	ds_write_b32 v54, v93
	s_waitcnt vmcnt(25)
	ds_write_b32 v56, v94
	s_waitcnt vmcnt(24)
	ds_write_b32 v58, v95
	s_waitcnt vmcnt(23)
	ds_write_b32 v60, v96
	s_waitcnt vmcnt(22)
	ds_write_b32 v62, v97
	s_waitcnt vmcnt(21)
	ds_write_b32 v64, v98
	s_waitcnt vmcnt(20)
	ds_write_b32 v66, v99
	s_waitcnt vmcnt(19)
	ds_write_b32 v68, v100
	s_waitcnt vmcnt(18)
	ds_write_b32 v70, v101
	s_waitcnt vmcnt(17)
	ds_write_b32 v72, v102
	s_waitcnt vmcnt(16)
	ds_write_b32 v74, v103
	s_waitcnt vmcnt(15)
	ds_write_b32 v186, v120
	s_waitcnt vmcnt(14)
	ds_write_b32 v188, v121
	s_waitcnt vmcnt(13)
	ds_write_b32 v190, v122
	s_waitcnt vmcnt(12)
	ds_write_b32 v192, v123
	s_waitcnt vmcnt(11)
	ds_write_b32 v194, v124
	s_waitcnt vmcnt(10)
	ds_write_b32 v196, v125
	s_waitcnt vmcnt(9)
	ds_write_b32 v198, v126
	s_waitcnt vmcnt(8)
	ds_write_b32 v200, v127
	s_waitcnt vmcnt(7)
	ds_write_b32 v202, v128
	s_waitcnt vmcnt(6)
	ds_write_b32 v204, v129
	s_waitcnt vmcnt(5)
	ds_write_b32 v206, v130
	s_waitcnt vmcnt(4)
	ds_write_b32 v208, v131
	s_waitcnt vmcnt(3)
	ds_write_b32 v210, v132
	s_waitcnt vmcnt(2)
	ds_write_b32 v212, v133
	s_waitcnt vmcnt(1)
	ds_write_b32 v214, v134
	s_waitcnt vmcnt(0)
	ds_write_b32 v216, v135
	s_waitcnt lgkmcnt(0)
	v_ashrrev_i32_e32 v17, 31, v16
	v_lshl_add_u64 v[2:3], v[16:17], 1, v[14:15]
	ds_read2_b32 v[16:17], v26 offset0:33 offset1:41
	ds_read2_b32 v[18:19], v26 offset1:8
	ds_read2_b32 v[44:45], v26 offset0:66 offset1:74
	ds_read2_b32 v[46:47], v26 offset0:99 offset1:107
	ds_read2_b32 v[48:49], v26 offset0:132 offset1:140
	ds_read2_b32 v[50:51], v26 offset0:165 offset1:173
	ds_read2_b32 v[52:53], v26 offset0:198 offset1:206
	ds_read2_b32 v[54:55], v26 offset0:231 offset1:239
	v_or_b32_e32 v7, v4, v25
	v_ashrrev_i32_e32 v9, 31, v4
	v_mov_b32_e32 v11, v5
	v_mul_lo_u32 v9, v9, v42
	v_mad_u64_u32 v[56:57], s[4:5], v7, v42, 0
	v_lshl_add_u64 v[2:3], v[2:3], 0, v[10:11]
	v_add_u32_e32 v57, v57, v9
	s_waitcnt lgkmcnt(6)
	v_cvt_pk_bf16_f32 v12, v18, v16
	s_waitcnt lgkmcnt(4)
	v_cvt_pk_bf16_f32 v13, v44, v46
	s_waitcnt lgkmcnt(2)
	v_cvt_pk_bf16_f32 v14, v48, v50
	s_waitcnt lgkmcnt(0)
	v_cvt_pk_bf16_f32 v15, v52, v54
	v_lshl_add_u64 v[56:57], v[56:57], 1, v[2:3]
	global_store_dwordx4 v[56:57], v[12:15], off sc1
	v_or_b32_e32 v7, v4, v27
	s_nop 0
	v_cvt_pk_bf16_f32 v12, v19, v17
	v_cvt_pk_bf16_f32 v13, v45, v47
	v_cvt_pk_bf16_f32 v14, v49, v51
	v_cvt_pk_bf16_f32 v15, v53, v55
	v_mad_u64_u32 v[16:17], s[4:5], v7, v42, 0
	ds_read2_b32 v[18:19], v26 offset0:16 offset1:24
	ds_read2_b32 v[44:45], v26 offset0:49 offset1:57
	ds_read2_b32 v[46:47], v26 offset0:82 offset1:90
	ds_read2_b32 v[48:49], v26 offset0:115 offset1:123
	ds_read2_b32 v[50:51], v26 offset0:148 offset1:156
	ds_read2_b32 v[52:53], v26 offset0:181 offset1:189
	ds_read2_b32 v[54:55], v26 offset0:214 offset1:222
	ds_read2_b32 v[56:57], v26 offset0:247 offset1:255
	v_add_u32_e32 v17, v17, v9
	v_lshl_add_u64 v[16:17], v[16:17], 1, v[2:3]
	v_or_b32_e32 v7, v4, v28
	global_store_dwordx4 v[16:17], v[12:15], off sc1
	v_mad_u64_u32 v[16:17], s[4:5], v7, v42, 0
	v_add_u32_e32 v17, v17, v9
	s_waitcnt lgkmcnt(6)
	v_cvt_pk_bf16_f32 v12, v18, v44
	s_waitcnt lgkmcnt(4)
	v_cvt_pk_bf16_f32 v13, v46, v48
	s_waitcnt lgkmcnt(2)
	v_cvt_pk_bf16_f32 v14, v50, v52
	s_waitcnt lgkmcnt(0)
	v_cvt_pk_bf16_f32 v15, v54, v56
	v_lshl_add_u64 v[16:17], v[16:17], 1, v[2:3]
	v_or_b32_e32 v4, v4, v29
	global_store_dwordx4 v[16:17], v[12:15], off sc1
	v_mad_u64_u32 v[16:17], s[4:5], v4, v42, 0
	v_add_u32_e32 v17, v17, v9
	v_cvt_pk_bf16_f32 v12, v19, v45
	v_cvt_pk_bf16_f32 v13, v47, v49
	v_cvt_pk_bf16_f32 v14, v51, v53
	v_cvt_pk_bf16_f32 v15, v55, v57
	v_lshl_add_u64 v[2:3], v[16:17], 1, v[2:3]
	global_store_dwordx4 v[2:3], v[12:15], off sc1
	s_waitcnt lgkmcnt(0)
	s_branch .LBB0_329

.LBB0_393:
	s_lshl_b32 s9, s5, 1
	s_lshl_b32 s11, s4, 1
	v_or_b32_e32 v9, s9, v1
	v_or_b32_e32 v11, s11, v0
	s_add_i32 s12, s9, 4
	s_add_i32 s13, s11, 4
	s_add_i32 s14, s9, 8
	s_add_i32 s15, s11, 8
	s_add_i32 s16, s9, 12
	s_add_i32 s17, s11, 12
	s_add_i32 s18, s9, 16
	s_add_i32 s19, s11, 16
	s_add_i32 s20, s9, 20
	s_add_i32 s21, s11, 20
	s_add_i32 s22, s9, 24
	s_add_i32 s23, s11, 24
	s_add_i32 s9, s9, 28
	s_add_i32 s11, s11, 28
	v_add_u32_e32 v17, v9, v7
	v_add_u32_e32 v40, v11, v16
	v_or_b32_e32 v70, s12, v1
	v_or_b32_e32 v71, s13, v0
	v_or_b32_e32 v72, s14, v1
	v_or_b32_e32 v73, s15, v0
	v_or_b32_e32 v74, s16, v1
	v_or_b32_e32 v75, s17, v0
	v_or_b32_e32 v76, s18, v1
	v_or_b32_e32 v77, s19, v0
	v_or_b32_e32 v78, s20, v1
	v_or_b32_e32 v79, s21, v0
	v_or_b32_e32 v80, s22, v1
	v_or_b32_e32 v81, s23, v0
	v_or_b32_e32 v82, s9, v1
	v_or_b32_e32 v83, s11, v0
	v_ashrrev_i32_e32 v42, 31, v40
	v_ashrrev_i32_e32 v43, 31, v17
	v_add_u32_e32 v44, v70, v7
	v_add_u32_e32 v45, v71, v16
	v_add_u32_e32 v46, v72, v7
	v_add_u32_e32 v48, v73, v16
	v_add_u32_e32 v50, v74, v7
	v_add_u32_e32 v52, v75, v16
	v_add_u32_e32 v54, v76, v7
	v_add_u32_e32 v56, v77, v16
	v_add_u32_e32 v58, v78, v7
	v_add_u32_e32 v60, v79, v16
	v_add_u32_e32 v62, v80, v7
	v_add_u32_e32 v64, v81, v16
	v_add_u32_e32 v66, v82, v7
	v_add_u32_e32 v68, v83, v16
	v_mul_lo_u32 v84, v3, v17
	v_mad_u64_u32 v[38:39], s[12:13], v2, v17, 0
	v_mul_lo_u32 v17, v13, v40
	v_mad_u64_u32 v[40:41], s[12:13], v12, v40, 0
	v_mul_lo_u32 v85, v2, v43
	v_mul_lo_u32 v86, v12, v42
	v_ashrrev_i32_e32 v87, 31, v45
	v_ashrrev_i32_e32 v88, 31, v44
	v_ashrrev_i32_e32 v91, 31, v48
	v_ashrrev_i32_e32 v92, 31, v46
	v_ashrrev_i32_e32 v95, 31, v52
	v_ashrrev_i32_e32 v96, 31, v50
	v_ashrrev_i32_e32 v99, 31, v56
	v_ashrrev_i32_e32 v100, 31, v54
	v_ashrrev_i32_e32 v103, 31, v60
	v_ashrrev_i32_e32 v104, 31, v58
	v_ashrrev_i32_e32 v107, 31, v64
	v_ashrrev_i32_e32 v108, 31, v62
	v_ashrrev_i32_e32 v111, 31, v68
	v_ashrrev_i32_e32 v112, 31, v66
	v_mul_lo_u32 v89, v3, v44
	v_mad_u64_u32 v[42:43], s[12:13], v2, v44, 0
	v_mul_lo_u32 v90, v13, v45
	v_mad_u64_u32 v[44:45], s[12:13], v12, v45, 0
	v_mul_lo_u32 v93, v3, v46
	v_mad_u64_u32 v[46:47], s[12:13], v2, v46, 0
	v_mul_lo_u32 v94, v13, v48
	v_mad_u64_u32 v[48:49], s[12:13], v12, v48, 0
	v_mul_lo_u32 v97, v3, v50
	v_mad_u64_u32 v[50:51], s[12:13], v2, v50, 0
	v_mul_lo_u32 v98, v13, v52
	v_mad_u64_u32 v[52:53], s[12:13], v12, v52, 0
	v_mul_lo_u32 v101, v3, v54
	v_mad_u64_u32 v[54:55], s[12:13], v2, v54, 0
	v_mul_lo_u32 v102, v13, v56
	v_mad_u64_u32 v[56:57], s[12:13], v12, v56, 0
	v_mul_lo_u32 v105, v3, v58
	v_mad_u64_u32 v[58:59], s[12:13], v2, v58, 0
	v_mul_lo_u32 v106, v13, v60
	v_mad_u64_u32 v[60:61], s[12:13], v12, v60, 0
	v_mul_lo_u32 v109, v3, v62
	v_mad_u64_u32 v[62:63], s[12:13], v2, v62, 0
	v_mul_lo_u32 v110, v13, v64
	v_mad_u64_u32 v[64:65], s[12:13], v12, v64, 0
	v_mul_lo_u32 v113, v3, v66
	v_mad_u64_u32 v[66:67], s[12:13], v2, v66, 0
	v_mul_lo_u32 v114, v13, v68
	v_mad_u64_u32 v[68:69], s[12:13], v12, v68, 0
	v_add3_u32 v39, v39, v85, v84
	v_add3_u32 v41, v41, v86, v17
	v_mul_lo_u32 v17, v2, v88
	v_mul_lo_u32 v84, v12, v87
	v_mul_lo_u32 v85, v2, v92
	v_mul_lo_u32 v86, v12, v91
	v_mul_lo_u32 v87, v2, v96
	v_mul_lo_u32 v88, v12, v95
	v_mul_lo_u32 v91, v2, v100
	v_mul_lo_u32 v92, v12, v99
	v_mul_lo_u32 v95, v2, v104
	v_mul_lo_u32 v96, v12, v103
	v_mul_lo_u32 v99, v2, v108
	v_mul_lo_u32 v100, v12, v107
	v_mul_lo_u32 v103, v2, v112
	v_mul_lo_u32 v104, v12, v111
	v_lshl_add_u64 v[40:41], v[40:41], 2, v[18:19]
	v_add3_u32 v43, v43, v17, v89
	v_add3_u32 v45, v45, v84, v90
	v_add3_u32 v47, v47, v85, v93
	v_add3_u32 v49, v49, v86, v94
	v_add3_u32 v51, v51, v87, v97
	v_add3_u32 v53, v53, v88, v98
	v_add3_u32 v55, v55, v91, v101
	v_add3_u32 v57, v57, v92, v102
	v_add3_u32 v59, v59, v95, v105
	v_add3_u32 v61, v61, v96, v106
	v_add3_u32 v63, v63, v99, v109
	v_add3_u32 v65, v65, v100, v110
	v_add3_u32 v67, v67, v103, v113
	v_add3_u32 v69, v69, v104, v114
	v_lshl_add_u64 v[38:39], v[38:39], 2, v[18:19]
	v_lshl_add_u64 v[44:45], v[44:45], 2, v[18:19]
	v_lshl_add_u64 v[42:43], v[42:43], 2, v[18:19]
	v_lshl_add_u64 v[48:49], v[48:49], 2, v[18:19]
	v_lshl_add_u64 v[46:47], v[46:47], 2, v[18:19]
	v_lshl_add_u64 v[52:53], v[52:53], 2, v[18:19]
	v_lshl_add_u64 v[50:51], v[50:51], 2, v[18:19]
	v_lshl_add_u64 v[56:57], v[56:57], 2, v[18:19]
	v_lshl_add_u64 v[54:55], v[54:55], 2, v[18:19]
	v_lshl_add_u64 v[60:61], v[60:61], 2, v[18:19]
	v_lshl_add_u64 v[58:59], v[58:59], 2, v[18:19]
	v_lshl_add_u64 v[64:65], v[64:65], 2, v[18:19]
	v_lshl_add_u64 v[62:63], v[62:63], 2, v[18:19]
	v_lshl_add_u64 v[68:69], v[68:69], 2, v[18:19]
	v_lshl_add_u64 v[66:67], v[66:67], 2, v[18:19]
	global_load_dword v17, v[40:41], off nt
	global_load_dword v84, v[38:39], off nt
	global_load_dword v85, v[44:45], off nt
	global_load_dword v86, v[42:43], off nt
	global_load_dword v87, v[48:49], off nt
	global_load_dword v88, v[46:47], off nt
	global_load_dword v89, v[52:53], off nt
	global_load_dword v90, v[50:51], off nt
	global_load_dword v91, v[56:57], off nt
	global_load_dword v92, v[54:55], off nt
	global_load_dword v93, v[60:61], off nt
	global_load_dword v94, v[58:59], off nt
	global_load_dword v95, v[64:65], off nt
	global_load_dword v96, v[62:63], off nt
	global_load_dword v97, v[68:69], off nt
	global_load_dword v98, v[66:67], off nt
	s_add_i32 s4, s4, 16
	s_add_i32 s5, s5, 16
	v_mad_u64_u32 v[38:39], s[12:13], v11, s1, v[6:7]
	v_mad_u64_u32 v[40:41], s[12:13], v9, s1, v[6:7]
	v_mad_u64_u32 v[42:43], s[12:13], v71, s1, v[6:7]
	v_mad_u64_u32 v[44:45], s[12:13], v70, s1, v[6:7]
	v_mad_u64_u32 v[46:47], s[12:13], v73, s1, v[6:7]
	v_mad_u64_u32 v[48:49], s[12:13], v72, s1, v[6:7]
	v_mad_u64_u32 v[50:51], s[12:13], v75, s1, v[6:7]
	v_mad_u64_u32 v[52:53], s[12:13], v74, s1, v[6:7]
	v_mad_u64_u32 v[54:55], s[12:13], v77, s1, v[6:7]
	v_mad_u64_u32 v[56:57], s[12:13], v76, s1, v[6:7]
	v_mad_u64_u32 v[58:59], s[12:13], v79, s1, v[6:7]
	v_mad_u64_u32 v[60:61], s[12:13], v78, s1, v[6:7]
	v_mad_u64_u32 v[62:63], s[12:13], v81, s1, v[6:7]
	v_mad_u64_u32 v[64:65], s[12:13], v80, s1, v[6:7]
	v_mad_u64_u32 v[66:67], s[12:13], v83, s1, v[6:7]
	v_mad_u64_u32 v[68:69], s[12:13], v82, s1, v[6:7]
	s_lshl_b32 s9, s5, 1
	s_lshl_b32 s11, s4, 1
	v_or_b32_e32 v9, s9, v1
	v_or_b32_e32 v11, s11, v0
	s_add_i32 s12, s9, 4
	s_add_i32 s13, s11, 4
	s_add_i32 s14, s9, 8
	s_add_i32 s15, s11, 8
	s_add_i32 s16, s9, 12
	s_add_i32 s17, s11, 12
	s_add_i32 s18, s9, 16
	s_add_i32 s19, s11, 16
	s_add_i32 s20, s9, 20
	s_add_i32 s21, s11, 20
	s_add_i32 s22, s9, 24
	s_add_i32 s23, s11, 24
	s_add_i32 s9, s9, 28
	s_add_i32 s11, s11, 28
	v_add_u32_e32 v120, v9, v7
	v_add_u32_e32 v188, v11, v16
	v_or_b32_e32 v70, s12, v1
	v_or_b32_e32 v71, s13, v0
	v_or_b32_e32 v72, s14, v1
	v_or_b32_e32 v73, s15, v0
	v_or_b32_e32 v74, s16, v1
	v_or_b32_e32 v75, s17, v0
	v_or_b32_e32 v76, s18, v1
	v_or_b32_e32 v77, s19, v0
	v_or_b32_e32 v78, s20, v1
	v_or_b32_e32 v79, s21, v0
	v_or_b32_e32 v80, s22, v1
	v_or_b32_e32 v81, s23, v0
	v_or_b32_e32 v82, s9, v1
	v_or_b32_e32 v83, s11, v0
	v_ashrrev_i32_e32 v190, 31, v188
	v_ashrrev_i32_e32 v191, 31, v120
	v_add_u32_e32 v192, v70, v7
	v_add_u32_e32 v193, v71, v16
	v_add_u32_e32 v194, v72, v7
	v_add_u32_e32 v196, v73, v16
	v_add_u32_e32 v198, v74, v7
	v_add_u32_e32 v200, v75, v16
	v_add_u32_e32 v202, v76, v7
	v_add_u32_e32 v204, v77, v16
	v_add_u32_e32 v206, v78, v7
	v_add_u32_e32 v208, v79, v16
	v_add_u32_e32 v210, v80, v7
	v_add_u32_e32 v212, v81, v16
	v_add_u32_e32 v214, v82, v7
	v_add_u32_e32 v216, v83, v16
	v_mul_lo_u32 v121, v3, v120
	v_mad_u64_u32 v[186:187], s[12:13], v2, v120, 0
	v_mul_lo_u32 v120, v13, v188
	v_mad_u64_u32 v[188:189], s[12:13], v12, v188, 0
	v_mul_lo_u32 v122, v2, v191
	v_mul_lo_u32 v123, v12, v190
	v_ashrrev_i32_e32 v124, 31, v193
	v_ashrrev_i32_e32 v125, 31, v192
	v_ashrrev_i32_e32 v128, 31, v196
	v_ashrrev_i32_e32 v129, 31, v194
	v_ashrrev_i32_e32 v132, 31, v200
	v_ashrrev_i32_e32 v133, 31, v198
	v_ashrrev_i32_e32 v99, 31, v204
	v_ashrrev_i32_e32 v100, 31, v202
	v_ashrrev_i32_e32 v103, 31, v208
	v_ashrrev_i32_e32 v104, 31, v206
	v_ashrrev_i32_e32 v107, 31, v212
	v_ashrrev_i32_e32 v108, 31, v210
	v_ashrrev_i32_e32 v111, 31, v216
	v_ashrrev_i32_e32 v112, 31, v214
	v_mul_lo_u32 v126, v3, v192
	v_mad_u64_u32 v[190:191], s[12:13], v2, v192, 0
	v_mul_lo_u32 v127, v13, v193
	v_mad_u64_u32 v[192:193], s[12:13], v12, v193, 0
	v_mul_lo_u32 v130, v3, v194
	v_mad_u64_u32 v[194:195], s[12:13], v2, v194, 0
	v_mul_lo_u32 v131, v13, v196
	v_mad_u64_u32 v[196:197], s[12:13], v12, v196, 0
	v_mul_lo_u32 v134, v3, v198
	v_mad_u64_u32 v[198:199], s[12:13], v2, v198, 0
	v_mul_lo_u32 v135, v13, v200
	v_mad_u64_u32 v[200:201], s[12:13], v12, v200, 0
	v_mul_lo_u32 v101, v3, v202
	v_mad_u64_u32 v[202:203], s[12:13], v2, v202, 0
	v_mul_lo_u32 v102, v13, v204
	v_mad_u64_u32 v[204:205], s[12:13], v12, v204, 0
	v_mul_lo_u32 v105, v3, v206
	v_mad_u64_u32 v[206:207], s[12:13], v2, v206, 0
	v_mul_lo_u32 v106, v13, v208
	v_mad_u64_u32 v[208:209], s[12:13], v12, v208, 0
	v_mul_lo_u32 v109, v3, v210
	v_mad_u64_u32 v[210:211], s[12:13], v2, v210, 0
	v_mul_lo_u32 v110, v13, v212
	v_mad_u64_u32 v[212:213], s[12:13], v12, v212, 0
	v_mul_lo_u32 v113, v3, v214
	v_mad_u64_u32 v[214:215], s[12:13], v2, v214, 0
	v_mul_lo_u32 v114, v13, v216
	v_mad_u64_u32 v[216:217], s[12:13], v12, v216, 0
	v_add3_u32 v187, v187, v122, v121
	v_add3_u32 v189, v189, v123, v120
	v_mul_lo_u32 v120, v2, v125
	v_mul_lo_u32 v121, v12, v124
	v_mul_lo_u32 v122, v2, v129
	v_mul_lo_u32 v123, v12, v128
	v_mul_lo_u32 v124, v2, v133
	v_mul_lo_u32 v125, v12, v132
	v_mul_lo_u32 v128, v2, v100
	v_mul_lo_u32 v129, v12, v99
	v_mul_lo_u32 v132, v2, v104
	v_mul_lo_u32 v133, v12, v103
	v_mul_lo_u32 v99, v2, v108
	v_mul_lo_u32 v100, v12, v107
	v_mul_lo_u32 v103, v2, v112
	v_mul_lo_u32 v104, v12, v111
	v_lshl_add_u64 v[188:189], v[188:189], 2, v[18:19]
	v_add3_u32 v191, v191, v120, v126
	v_add3_u32 v193, v193, v121, v127
	v_add3_u32 v195, v195, v122, v130
	v_add3_u32 v197, v197, v123, v131
	v_add3_u32 v199, v199, v124, v134
	v_add3_u32 v201, v201, v125, v135
	v_add3_u32 v203, v203, v128, v101
	v_add3_u32 v205, v205, v129, v102
	v_add3_u32 v207, v207, v132, v105
	v_add3_u32 v209, v209, v133, v106
	v_add3_u32 v211, v211, v99, v109
	v_add3_u32 v213, v213, v100, v110
	v_add3_u32 v215, v215, v103, v113
	v_add3_u32 v217, v217, v104, v114
	v_lshl_add_u64 v[186:187], v[186:187], 2, v[18:19]
	v_lshl_add_u64 v[192:193], v[192:193], 2, v[18:19]
	v_lshl_add_u64 v[190:191], v[190:191], 2, v[18:19]
	v_lshl_add_u64 v[196:197], v[196:197], 2, v[18:19]
	v_lshl_add_u64 v[194:195], v[194:195], 2, v[18:19]
	v_lshl_add_u64 v[200:201], v[200:201], 2, v[18:19]
	v_lshl_add_u64 v[198:199], v[198:199], 2, v[18:19]
	v_lshl_add_u64 v[204:205], v[204:205], 2, v[18:19]
	v_lshl_add_u64 v[202:203], v[202:203], 2, v[18:19]
	v_lshl_add_u64 v[208:209], v[208:209], 2, v[18:19]
	v_lshl_add_u64 v[206:207], v[206:207], 2, v[18:19]
	v_lshl_add_u64 v[212:213], v[212:213], 2, v[18:19]
	v_lshl_add_u64 v[210:211], v[210:211], 2, v[18:19]
	v_lshl_add_u64 v[216:217], v[216:217], 2, v[18:19]
	v_lshl_add_u64 v[214:215], v[214:215], 2, v[18:19]
	global_load_dword v120, v[188:189], off nt
	global_load_dword v121, v[186:187], off nt
	global_load_dword v122, v[192:193], off nt
	global_load_dword v123, v[190:191], off nt
	global_load_dword v124, v[196:197], off nt
	global_load_dword v125, v[194:195], off nt
	global_load_dword v126, v[200:201], off nt
	global_load_dword v127, v[198:199], off nt
	global_load_dword v128, v[204:205], off nt
	global_load_dword v129, v[202:203], off nt
	global_load_dword v130, v[208:209], off nt
	global_load_dword v131, v[206:207], off nt
	global_load_dword v132, v[212:213], off nt
	global_load_dword v133, v[210:211], off nt
	global_load_dword v134, v[216:217], off nt
	global_load_dword v135, v[214:215], off nt
	s_add_i32 s4, s4, 16
	s_add_i32 s5, s5, 16
	s_mov_b32 s8, 0
	v_mad_u64_u32 v[186:187], s[12:13], v11, s1, v[6:7]
	v_mad_u64_u32 v[188:189], s[12:13], v9, s1, v[6:7]
	v_mad_u64_u32 v[190:191], s[12:13], v71, s1, v[6:7]
	v_mad_u64_u32 v[192:193], s[12:13], v70, s1, v[6:7]
	v_mad_u64_u32 v[194:195], s[12:13], v73, s1, v[6:7]
	v_mad_u64_u32 v[196:197], s[12:13], v72, s1, v[6:7]
	v_mad_u64_u32 v[198:199], s[12:13], v75, s1, v[6:7]
	v_mad_u64_u32 v[200:201], s[12:13], v74, s1, v[6:7]
	v_mad_u64_u32 v[202:203], s[12:13], v77, s1, v[6:7]
	v_mad_u64_u32 v[204:205], s[12:13], v76, s1, v[6:7]
	v_mad_u64_u32 v[206:207], s[12:13], v79, s1, v[6:7]
	v_mad_u64_u32 v[208:209], s[12:13], v78, s1, v[6:7]
	v_mad_u64_u32 v[210:211], s[12:13], v81, s1, v[6:7]
	v_mad_u64_u32 v[212:213], s[12:13], v80, s1, v[6:7]
	v_mad_u64_u32 v[214:215], s[12:13], v83, s1, v[6:7]
	v_mad_u64_u32 v[216:217], s[12:13], v82, s1, v[6:7]
	s_waitcnt vmcnt(31)
	ds_write_b32 v38, v17
	s_waitcnt vmcnt(30)
	ds_write_b32 v40, v84
	s_waitcnt vmcnt(29)
	ds_write_b32 v42, v85
	s_waitcnt vmcnt(28)
	ds_write_b32 v44, v86
	s_waitcnt vmcnt(27)
	ds_write_b32 v46, v87
	s_waitcnt vmcnt(26)
	ds_write_b32 v48, v88
	s_waitcnt vmcnt(25)
	ds_write_b32 v50, v89
	s_waitcnt vmcnt(24)
	ds_write_b32 v52, v90
	s_waitcnt vmcnt(23)
	ds_write_b32 v54, v91
	s_waitcnt vmcnt(22)
	ds_write_b32 v56, v92
	s_waitcnt vmcnt(21)
	ds_write_b32 v58, v93
	s_waitcnt vmcnt(20)
	ds_write_b32 v60, v94
	s_waitcnt vmcnt(19)
	ds_write_b32 v62, v95
	s_waitcnt vmcnt(18)
	ds_write_b32 v64, v96
	s_waitcnt vmcnt(17)
	ds_write_b32 v66, v97
	s_waitcnt vmcnt(16)
	ds_write_b32 v68, v98
	s_waitcnt vmcnt(15)
	ds_write_b32 v186, v120
	s_waitcnt vmcnt(14)
	ds_write_b32 v188, v121
	s_waitcnt vmcnt(13)
	ds_write_b32 v190, v122
	s_waitcnt vmcnt(12)
	ds_write_b32 v192, v123
	s_waitcnt vmcnt(11)
	ds_write_b32 v194, v124
	s_waitcnt vmcnt(10)
	ds_write_b32 v196, v125
	s_waitcnt vmcnt(9)
	ds_write_b32 v198, v126
	s_waitcnt vmcnt(8)
	ds_write_b32 v200, v127
	s_waitcnt vmcnt(7)
	ds_write_b32 v202, v128
	s_waitcnt vmcnt(6)
	ds_write_b32 v204, v129
	s_waitcnt vmcnt(5)
	ds_write_b32 v206, v130
	s_waitcnt vmcnt(4)
	ds_write_b32 v208, v131
	s_waitcnt vmcnt(3)
	ds_write_b32 v210, v132
	s_waitcnt vmcnt(2)
	ds_write_b32 v212, v133
	s_waitcnt vmcnt(1)
	ds_write_b32 v214, v134
	s_waitcnt vmcnt(0)
	ds_write_b32 v216, v135
	s_waitcnt lgkmcnt(0)
	v_ashrrev_i32_e32 v17, 31, v16
	v_lshl_add_u64 v[2:3], v[16:17], 1, v[14:15]
	ds_read2_b32 v[16:17], v21 offset0:33 offset1:41
	ds_read2_b32 v[18:19], v21 offset1:8
	ds_read2_b32 v[38:39], v21 offset0:66 offset1:74
	ds_read2_b32 v[40:41], v21 offset0:99 offset1:107
	ds_read2_b32 v[42:43], v21 offset0:132 offset1:140
	ds_read2_b32 v[44:45], v21 offset0:165 offset1:173
	ds_read2_b32 v[46:47], v21 offset0:198 offset1:206
	ds_read2_b32 v[48:49], v21 offset0:231 offset1:239
	v_or_b32_e32 v7, v4, v20
	v_ashrrev_i32_e32 v9, 31, v4
	v_mov_b32_e32 v11, v5
	v_mul_lo_u32 v9, v9, v37
	v_mad_u64_u32 v[50:51], s[4:5], v7, v37, 0
	v_lshl_add_u64 v[2:3], v[2:3], 0, v[10:11]
	v_add_u32_e32 v51, v51, v9
	s_waitcnt lgkmcnt(6)
	v_cvt_pk_bf16_f32 v12, v18, v16
	s_waitcnt lgkmcnt(4)
	v_cvt_pk_bf16_f32 v13, v38, v40
	s_waitcnt lgkmcnt(2)
	v_cvt_pk_bf16_f32 v14, v42, v44
	s_waitcnt lgkmcnt(0)
	v_cvt_pk_bf16_f32 v15, v46, v48
	v_lshl_add_u64 v[50:51], v[50:51], 1, v[2:3]
	global_store_dwordx4 v[50:51], v[12:15], off sc1
	v_or_b32_e32 v7, v4, v22
	s_nop 0
	v_cvt_pk_bf16_f32 v12, v19, v17
	v_cvt_pk_bf16_f32 v13, v39, v41
	v_cvt_pk_bf16_f32 v14, v43, v45
	v_cvt_pk_bf16_f32 v15, v47, v49
	v_mad_u64_u32 v[16:17], s[4:5], v7, v37, 0
	ds_read2_b32 v[18:19], v21 offset0:16 offset1:24
	ds_read2_b32 v[38:39], v21 offset0:49 offset1:57
	ds_read2_b32 v[40:41], v21 offset0:82 offset1:90
	ds_read2_b32 v[42:43], v21 offset0:115 offset1:123
	ds_read2_b32 v[44:45], v21 offset0:148 offset1:156
	ds_read2_b32 v[46:47], v21 offset0:181 offset1:189
	ds_read2_b32 v[48:49], v21 offset0:214 offset1:222
	ds_read2_b32 v[50:51], v21 offset0:247 offset1:255
	v_add_u32_e32 v17, v17, v9
	v_lshl_add_u64 v[16:17], v[16:17], 1, v[2:3]
	v_or_b32_e32 v7, v4, v23
	global_store_dwordx4 v[16:17], v[12:15], off sc1
	v_mad_u64_u32 v[16:17], s[4:5], v7, v37, 0
	v_add_u32_e32 v17, v17, v9
	s_waitcnt lgkmcnt(6)
	v_cvt_pk_bf16_f32 v12, v18, v38
	s_waitcnt lgkmcnt(4)
	v_cvt_pk_bf16_f32 v13, v40, v42
	s_waitcnt lgkmcnt(2)
	v_cvt_pk_bf16_f32 v14, v44, v46
	s_waitcnt lgkmcnt(0)
	v_cvt_pk_bf16_f32 v15, v48, v50
	v_lshl_add_u64 v[16:17], v[16:17], 1, v[2:3]
	v_or_b32_e32 v4, v4, v24
	global_store_dwordx4 v[16:17], v[12:15], off sc1
	v_mad_u64_u32 v[16:17], s[4:5], v4, v37, 0
	v_add_u32_e32 v17, v17, v9
	v_cvt_pk_bf16_f32 v12, v19, v39
	v_cvt_pk_bf16_f32 v13, v41, v43
	v_cvt_pk_bf16_f32 v14, v45, v47
	v_cvt_pk_bf16_f32 v15, v49, v51
	v_lshl_add_u64 v[2:3], v[16:17], 1, v[2:3]
	global_store_dwordx4 v[2:3], v[12:15], off sc1
	s_waitcnt lgkmcnt(0)
	s_branch .LBB0_378
